# GU GEMM: epilogues of the two half-workgroups no longer aligned (ALIGN barrier and the trailing restore barrier removed, one leading barrier after the last unit): each swiglu epilogue overlaps the oth
# baseline (speedup 1.0000x reference)
.LBB0_288:
.LBB0_290:
	s_mov_b64 s[22:23], -1
	s_and_b64 vcc, exec, s[0:1]
	v_lshl_add_u32 v149, s11, 8, v1
	v_lshl_or_b32 v144, s10, 7, v147
	v_ashrrev_i32_e32 v145, 31, v144
	v_mov_b64_e32 v[142:143], s[34:35]
	v_lshlrev_b64 v[144:145], 1, v[144:145]
	v_mad_i64_i32 v[214:215], s[10:11], v149, s87, v[142:143]
	v_or_b32_e32 v216, 16, v149
	v_mad_i64_i32 v[216:217], s[10:11], v216, s87, v[142:143]
	v_or_b32_e32 v218, 32, v149
	v_mad_i64_i32 v[218:219], s[10:11], v218, s87, v[142:143]
	v_or_b32_e32 v220, 48, v149
	v_mad_i64_i32 v[220:221], s[10:11], v220, s87, v[142:143]
	v_add_u32_e32 v222, 0x80, v149
	v_mad_i64_i32 v[222:223], s[10:11], v222, s87, v[142:143]
	v_add_u32_e32 v224, 0x90, v149
	v_mad_i64_i32 v[224:225], s[10:11], v224, s87, v[142:143]
	v_add_u32_e32 v226, 0xa0, v149
	v_mad_i64_i32 v[226:227], s[10:11], v226, s87, v[142:143]
	v_add_u32_e32 v236, 0xb0, v149
	v_mad_i64_i32 v[236:237], s[10:11], v236, s87, v[142:143]
	v_lshl_add_u64 v[214:215], v[214:215], 0, v[144:145]
	v_lshl_add_u64 v[216:217], v[216:217], 0, v[144:145]
	v_lshl_add_u64 v[218:219], v[218:219], 0, v[144:145]
	v_lshl_add_u64 v[220:221], v[220:221], 0, v[144:145]
	v_lshl_add_u64 v[222:223], v[222:223], 0, v[144:145]
	v_lshl_add_u64 v[224:225], v[224:225], 0, v[144:145]
	v_lshl_add_u64 v[226:227], v[226:227], 0, v[144:145]
	v_lshl_add_u64 v[236:237], v[236:237], 0, v[144:145]
	v_mul_f32_e32 v150, 0xbfb8aa3b, v122
	v_mul_f32_e32 v152, 0xbfb8aa3b, v124
	v_mul_f32_e32 v151, 0xbfb8aa3b, v123
	v_mul_f32_e32 v153, 0xbfb8aa3b, v125
	v_exp_f32_e32 v150, v150
	v_exp_f32_e32 v152, v152
	v_exp_f32_e32 v151, v151
	v_exp_f32_e32 v153, v153
	v_add_f32_e32 v150, 1.0, v150
	v_add_f32_e32 v152, 1.0, v152
	v_add_f32_e32 v151, 1.0, v151
	v_add_f32_e32 v153, 1.0, v153
	v_rcp_f32_e32 v150, v150
	v_rcp_f32_e32 v152, v152
	v_rcp_f32_e32 v151, v151
	v_rcp_f32_e32 v153, v153
	v_pk_mul_f32 v[122:123], v[122:123], v[150:151]
	v_pk_mul_f32 v[124:125], v[124:125], v[152:153]
	v_pk_mul_f32 v[122:123], v[126:127], v[122:123]
	v_pk_mul_f32 v[124:125], v[128:129], v[124:125]
	v_cvt_pk_bf16_f32 v160, v122, v123
	v_cvt_pk_bf16_f32 v161, v124, v125
	v_mul_f32_e32 v154, 0xbfb8aa3b, v118
	v_mul_f32_e32 v156, 0xbfb8aa3b, v120
	v_mul_f32_e32 v155, 0xbfb8aa3b, v119
	v_mul_f32_e32 v157, 0xbfb8aa3b, v121
	v_exp_f32_e32 v154, v154
	v_exp_f32_e32 v156, v156
	v_exp_f32_e32 v155, v155
	v_exp_f32_e32 v157, v157
	v_add_f32_e32 v154, 1.0, v154
	v_add_f32_e32 v156, 1.0, v156
	v_add_f32_e32 v155, 1.0, v155
	v_add_f32_e32 v157, 1.0, v157
	v_rcp_f32_e32 v154, v154
	v_rcp_f32_e32 v156, v156
	v_rcp_f32_e32 v155, v155
	v_rcp_f32_e32 v157, v157
	v_pk_mul_f32 v[118:119], v[118:119], v[154:155]
	v_pk_mul_f32 v[120:121], v[120:121], v[156:157]
	v_pk_mul_f32 v[118:119], v[114:115], v[118:119]
	v_pk_mul_f32 v[120:121], v[116:117], v[120:121]
	v_cvt_pk_bf16_f32 v162, v118, v119
	v_cvt_pk_bf16_f32 v163, v120, v121
	global_store_dwordx4 v[214:215], v[160:163], off nt
	v_mul_f32_e32 v150, 0xbfb8aa3b, v110
	v_mul_f32_e32 v152, 0xbfb8aa3b, v112
	v_mul_f32_e32 v151, 0xbfb8aa3b, v111
	v_mul_f32_e32 v153, 0xbfb8aa3b, v113
	v_exp_f32_e32 v150, v150
	v_exp_f32_e32 v152, v152
	v_exp_f32_e32 v151, v151
	v_exp_f32_e32 v153, v153
	v_add_f32_e32 v150, 1.0, v150
	v_add_f32_e32 v152, 1.0, v152
	v_add_f32_e32 v151, 1.0, v151
	v_add_f32_e32 v153, 1.0, v153
	v_rcp_f32_e32 v150, v150
	v_rcp_f32_e32 v152, v152
	v_rcp_f32_e32 v151, v151
	v_rcp_f32_e32 v153, v153
	v_pk_mul_f32 v[110:111], v[110:111], v[150:151]
	v_pk_mul_f32 v[112:113], v[112:113], v[152:153]
	v_pk_mul_f32 v[110:111], v[106:107], v[110:111]
	v_pk_mul_f32 v[112:113], v[108:109], v[112:113]
	v_cvt_pk_bf16_f32 v164, v110, v111
	v_cvt_pk_bf16_f32 v165, v112, v113
	v_mul_f32_e32 v154, 0xbfb8aa3b, v102
	v_mul_f32_e32 v156, 0xbfb8aa3b, v104
	v_mul_f32_e32 v155, 0xbfb8aa3b, v103
	v_mul_f32_e32 v157, 0xbfb8aa3b, v105
	v_exp_f32_e32 v154, v154
	v_exp_f32_e32 v156, v156
	v_exp_f32_e32 v155, v155
	v_exp_f32_e32 v157, v157
	v_add_f32_e32 v154, 1.0, v154
	v_add_f32_e32 v156, 1.0, v156
	v_add_f32_e32 v155, 1.0, v155
	v_add_f32_e32 v157, 1.0, v157
	v_rcp_f32_e32 v154, v154
	v_rcp_f32_e32 v156, v156
	v_rcp_f32_e32 v155, v155
	v_rcp_f32_e32 v157, v157
	v_pk_mul_f32 v[102:103], v[102:103], v[154:155]
	v_pk_mul_f32 v[104:105], v[104:105], v[156:157]
	v_pk_mul_f32 v[102:103], v[98:99], v[102:103]
	v_pk_mul_f32 v[104:105], v[100:101], v[104:105]
	v_cvt_pk_bf16_f32 v166, v102, v103
	v_cvt_pk_bf16_f32 v167, v104, v105
	global_store_dwordx4 v[216:217], v[164:167], off nt
	v_mul_f32_e32 v150, 0xbfb8aa3b, v94
	v_mul_f32_e32 v152, 0xbfb8aa3b, v96
	v_mul_f32_e32 v151, 0xbfb8aa3b, v95
	v_mul_f32_e32 v153, 0xbfb8aa3b, v97
	v_exp_f32_e32 v150, v150
	v_exp_f32_e32 v152, v152
	v_exp_f32_e32 v151, v151
	v_exp_f32_e32 v153, v153
	v_add_f32_e32 v150, 1.0, v150
	v_add_f32_e32 v152, 1.0, v152
	v_add_f32_e32 v151, 1.0, v151
	v_add_f32_e32 v153, 1.0, v153
	v_rcp_f32_e32 v150, v150
	v_rcp_f32_e32 v152, v152
	v_rcp_f32_e32 v151, v151
	v_rcp_f32_e32 v153, v153
	v_pk_mul_f32 v[94:95], v[94:95], v[150:151]
	v_pk_mul_f32 v[96:97], v[96:97], v[152:153]
	v_pk_mul_f32 v[94:95], v[90:91], v[94:95]
	v_pk_mul_f32 v[96:97], v[92:93], v[96:97]
	v_cvt_pk_bf16_f32 v168, v94, v95
	v_cvt_pk_bf16_f32 v169, v96, v97
	v_mul_f32_e32 v154, 0xbfb8aa3b, v86
	v_mul_f32_e32 v156, 0xbfb8aa3b, v88
	v_mul_f32_e32 v155, 0xbfb8aa3b, v87
	v_mul_f32_e32 v157, 0xbfb8aa3b, v89
	v_exp_f32_e32 v154, v154
	v_exp_f32_e32 v156, v156
	v_exp_f32_e32 v155, v155
	v_exp_f32_e32 v157, v157
	v_add_f32_e32 v154, 1.0, v154
	v_add_f32_e32 v156, 1.0, v156
	v_add_f32_e32 v155, 1.0, v155
	v_add_f32_e32 v157, 1.0, v157
	v_rcp_f32_e32 v154, v154
	v_rcp_f32_e32 v156, v156
	v_rcp_f32_e32 v155, v155
	v_rcp_f32_e32 v157, v157
	v_pk_mul_f32 v[86:87], v[86:87], v[154:155]
	v_pk_mul_f32 v[88:89], v[88:89], v[156:157]
	v_pk_mul_f32 v[86:87], v[82:83], v[86:87]
	v_pk_mul_f32 v[88:89], v[84:85], v[88:89]
	v_cvt_pk_bf16_f32 v170, v86, v87
	v_cvt_pk_bf16_f32 v171, v88, v89
	global_store_dwordx4 v[218:219], v[168:171], off nt
	v_mul_f32_e32 v150, 0xbfb8aa3b, v78
	v_mul_f32_e32 v152, 0xbfb8aa3b, v80
	v_mul_f32_e32 v151, 0xbfb8aa3b, v79
	v_mul_f32_e32 v153, 0xbfb8aa3b, v81
	v_exp_f32_e32 v150, v150
	v_exp_f32_e32 v152, v152
	v_exp_f32_e32 v151, v151
	v_exp_f32_e32 v153, v153
	v_add_f32_e32 v150, 1.0, v150
	v_add_f32_e32 v152, 1.0, v152
	v_add_f32_e32 v151, 1.0, v151
	v_add_f32_e32 v153, 1.0, v153
	v_rcp_f32_e32 v150, v150
	v_rcp_f32_e32 v152, v152
	v_rcp_f32_e32 v151, v151
	v_rcp_f32_e32 v153, v153
	v_pk_mul_f32 v[78:79], v[78:79], v[150:151]
	v_pk_mul_f32 v[80:81], v[80:81], v[152:153]
	v_pk_mul_f32 v[78:79], v[74:75], v[78:79]
	v_pk_mul_f32 v[80:81], v[76:77], v[80:81]
	v_cvt_pk_bf16_f32 v172, v78, v79
	v_cvt_pk_bf16_f32 v173, v80, v81
	v_mul_f32_e32 v154, 0xbfb8aa3b, v70
	v_mul_f32_e32 v156, 0xbfb8aa3b, v72
	v_mul_f32_e32 v155, 0xbfb8aa3b, v71
	v_mul_f32_e32 v157, 0xbfb8aa3b, v73
	v_exp_f32_e32 v154, v154
	v_exp_f32_e32 v156, v156
	v_exp_f32_e32 v155, v155
	v_exp_f32_e32 v157, v157
	v_add_f32_e32 v154, 1.0, v154
	v_add_f32_e32 v156, 1.0, v156
	v_add_f32_e32 v155, 1.0, v155
	v_add_f32_e32 v157, 1.0, v157
	v_rcp_f32_e32 v154, v154
	v_rcp_f32_e32 v156, v156
	v_rcp_f32_e32 v155, v155
	v_rcp_f32_e32 v157, v157
	v_pk_mul_f32 v[70:71], v[70:71], v[154:155]
	v_pk_mul_f32 v[72:73], v[72:73], v[156:157]
	v_pk_mul_f32 v[70:71], v[66:67], v[70:71]
	v_pk_mul_f32 v[72:73], v[68:69], v[72:73]
	v_cvt_pk_bf16_f32 v174, v70, v71
	v_cvt_pk_bf16_f32 v175, v72, v73
	global_store_dwordx4 v[220:221], v[172:175], off nt
	v_mul_f32_e32 v150, 0xbfb8aa3b, v62
	v_mul_f32_e32 v152, 0xbfb8aa3b, v64
	v_mul_f32_e32 v151, 0xbfb8aa3b, v63
	v_mul_f32_e32 v153, 0xbfb8aa3b, v65
	v_exp_f32_e32 v150, v150
	v_exp_f32_e32 v152, v152
	v_exp_f32_e32 v151, v151
	v_exp_f32_e32 v153, v153
	v_add_f32_e32 v150, 1.0, v150
	v_add_f32_e32 v152, 1.0, v152
	v_add_f32_e32 v151, 1.0, v151
	v_add_f32_e32 v153, 1.0, v153
	v_rcp_f32_e32 v150, v150
	v_rcp_f32_e32 v152, v152
	v_rcp_f32_e32 v151, v151
	v_rcp_f32_e32 v153, v153
	v_pk_mul_f32 v[62:63], v[62:63], v[150:151]
	v_pk_mul_f32 v[64:65], v[64:65], v[152:153]
	v_pk_mul_f32 v[62:63], v[58:59], v[62:63]
	v_pk_mul_f32 v[64:65], v[60:61], v[64:65]
	v_cvt_pk_bf16_f32 v176, v62, v63
	v_cvt_pk_bf16_f32 v177, v64, v65
	v_mul_f32_e32 v154, 0xbfb8aa3b, v54
	v_mul_f32_e32 v156, 0xbfb8aa3b, v56
	v_mul_f32_e32 v155, 0xbfb8aa3b, v55
	v_mul_f32_e32 v157, 0xbfb8aa3b, v57
	v_exp_f32_e32 v154, v154
	v_exp_f32_e32 v156, v156
	v_exp_f32_e32 v155, v155
	v_exp_f32_e32 v157, v157
	v_add_f32_e32 v154, 1.0, v154
	v_add_f32_e32 v156, 1.0, v156
	v_add_f32_e32 v155, 1.0, v155
	v_add_f32_e32 v157, 1.0, v157
	v_rcp_f32_e32 v154, v154
	v_rcp_f32_e32 v156, v156
	v_rcp_f32_e32 v155, v155
	v_rcp_f32_e32 v157, v157
	v_pk_mul_f32 v[54:55], v[54:55], v[154:155]
	v_pk_mul_f32 v[56:57], v[56:57], v[156:157]
	v_pk_mul_f32 v[54:55], v[50:51], v[54:55]
	v_pk_mul_f32 v[56:57], v[52:53], v[56:57]
	v_cvt_pk_bf16_f32 v178, v54, v55
	v_cvt_pk_bf16_f32 v179, v56, v57
	global_store_dwordx4 v[222:223], v[176:179], off nt
	v_mul_f32_e32 v150, 0xbfb8aa3b, v46
	v_mul_f32_e32 v152, 0xbfb8aa3b, v48
	v_mul_f32_e32 v151, 0xbfb8aa3b, v47
	v_mul_f32_e32 v153, 0xbfb8aa3b, v49
	v_exp_f32_e32 v150, v150
	v_exp_f32_e32 v152, v152
	v_exp_f32_e32 v151, v151
	v_exp_f32_e32 v153, v153
	v_add_f32_e32 v150, 1.0, v150
	v_add_f32_e32 v152, 1.0, v152
	v_add_f32_e32 v151, 1.0, v151
	v_add_f32_e32 v153, 1.0, v153
	v_rcp_f32_e32 v150, v150
	v_rcp_f32_e32 v152, v152
	v_rcp_f32_e32 v151, v151
	v_rcp_f32_e32 v153, v153
	v_pk_mul_f32 v[46:47], v[46:47], v[150:151]
	v_pk_mul_f32 v[48:49], v[48:49], v[152:153]
	v_pk_mul_f32 v[46:47], v[42:43], v[46:47]
	v_pk_mul_f32 v[48:49], v[44:45], v[48:49]
	v_cvt_pk_bf16_f32 v180, v46, v47
	v_cvt_pk_bf16_f32 v181, v48, v49
	v_mul_f32_e32 v154, 0xbfb8aa3b, v38
	v_mul_f32_e32 v156, 0xbfb8aa3b, v40
	v_mul_f32_e32 v155, 0xbfb8aa3b, v39
	v_mul_f32_e32 v157, 0xbfb8aa3b, v41
	v_exp_f32_e32 v154, v154
	v_exp_f32_e32 v156, v156
	v_exp_f32_e32 v155, v155
	v_exp_f32_e32 v157, v157
	v_add_f32_e32 v154, 1.0, v154
	v_add_f32_e32 v156, 1.0, v156
	v_add_f32_e32 v155, 1.0, v155
	v_add_f32_e32 v157, 1.0, v157
	v_rcp_f32_e32 v154, v154
	v_rcp_f32_e32 v156, v156
	v_rcp_f32_e32 v155, v155
	v_rcp_f32_e32 v157, v157
	v_pk_mul_f32 v[38:39], v[38:39], v[154:155]
	v_pk_mul_f32 v[40:41], v[40:41], v[156:157]
	v_pk_mul_f32 v[38:39], v[34:35], v[38:39]
	v_pk_mul_f32 v[40:41], v[36:37], v[40:41]
	v_cvt_pk_bf16_f32 v182, v38, v39
	v_cvt_pk_bf16_f32 v183, v40, v41
	global_store_dwordx4 v[224:225], v[180:183], off nt
	v_mul_f32_e32 v150, 0xbfb8aa3b, v30
	v_mul_f32_e32 v152, 0xbfb8aa3b, v32
	v_mul_f32_e32 v151, 0xbfb8aa3b, v31
	v_mul_f32_e32 v153, 0xbfb8aa3b, v33
	v_exp_f32_e32 v150, v150
	v_exp_f32_e32 v152, v152
	v_exp_f32_e32 v151, v151
	v_exp_f32_e32 v153, v153
	v_add_f32_e32 v150, 1.0, v150
	v_add_f32_e32 v152, 1.0, v152
	v_add_f32_e32 v151, 1.0, v151
	v_add_f32_e32 v153, 1.0, v153
	v_rcp_f32_e32 v150, v150
	v_rcp_f32_e32 v152, v152
	v_rcp_f32_e32 v151, v151
	v_rcp_f32_e32 v153, v153
	v_pk_mul_f32 v[30:31], v[30:31], v[150:151]
	v_pk_mul_f32 v[32:33], v[32:33], v[152:153]
	v_pk_mul_f32 v[30:31], v[26:27], v[30:31]
	v_pk_mul_f32 v[32:33], v[28:29], v[32:33]
	v_cvt_pk_bf16_f32 v184, v30, v31
	v_cvt_pk_bf16_f32 v185, v32, v33
	v_mul_f32_e32 v154, 0xbfb8aa3b, v22
	v_mul_f32_e32 v156, 0xbfb8aa3b, v24
	v_mul_f32_e32 v155, 0xbfb8aa3b, v23
	v_mul_f32_e32 v157, 0xbfb8aa3b, v25
	v_exp_f32_e32 v154, v154
	v_exp_f32_e32 v156, v156
	v_exp_f32_e32 v155, v155
	v_exp_f32_e32 v157, v157
	v_add_f32_e32 v154, 1.0, v154
	v_add_f32_e32 v156, 1.0, v156
	v_add_f32_e32 v155, 1.0, v155
	v_add_f32_e32 v157, 1.0, v157
	v_rcp_f32_e32 v154, v154
	v_rcp_f32_e32 v156, v156
	v_rcp_f32_e32 v155, v155
	v_rcp_f32_e32 v157, v157
	v_pk_mul_f32 v[22:23], v[22:23], v[154:155]
	v_pk_mul_f32 v[24:25], v[24:25], v[156:157]
	v_pk_mul_f32 v[22:23], v[18:19], v[22:23]
	v_pk_mul_f32 v[24:25], v[20:21], v[24:25]
	v_cvt_pk_bf16_f32 v186, v22, v23
	v_cvt_pk_bf16_f32 v187, v24, v25
	global_store_dwordx4 v[226:227], v[184:187], off nt
	v_mul_f32_e32 v150, 0xbfb8aa3b, v14
	v_mul_f32_e32 v152, 0xbfb8aa3b, v16
	v_mul_f32_e32 v151, 0xbfb8aa3b, v15
	v_mul_f32_e32 v153, 0xbfb8aa3b, v17
	v_exp_f32_e32 v150, v150
	v_exp_f32_e32 v152, v152
	v_exp_f32_e32 v151, v151
	v_exp_f32_e32 v153, v153
	v_add_f32_e32 v150, 1.0, v150
	v_add_f32_e32 v152, 1.0, v152
	v_add_f32_e32 v151, 1.0, v151
	v_add_f32_e32 v153, 1.0, v153
	v_rcp_f32_e32 v150, v150
	v_rcp_f32_e32 v152, v152
	v_rcp_f32_e32 v151, v151
	v_rcp_f32_e32 v153, v153
	v_pk_mul_f32 v[14:15], v[14:15], v[150:151]
	v_pk_mul_f32 v[16:17], v[16:17], v[152:153]
	v_pk_mul_f32 v[14:15], v[10:11], v[14:15]
	v_pk_mul_f32 v[16:17], v[12:13], v[16:17]
	v_cvt_pk_bf16_f32 v188, v14, v15
	v_cvt_pk_bf16_f32 v189, v16, v17
	v_mul_f32_e32 v154, 0xbfb8aa3b, v6
	v_mul_f32_e32 v156, 0xbfb8aa3b, v8
	v_mul_f32_e32 v155, 0xbfb8aa3b, v7
	v_mul_f32_e32 v157, 0xbfb8aa3b, v9
	v_exp_f32_e32 v154, v154
	v_exp_f32_e32 v156, v156
	v_exp_f32_e32 v155, v155
	v_exp_f32_e32 v157, v157
	v_add_f32_e32 v154, 1.0, v154
	v_add_f32_e32 v156, 1.0, v156
	v_add_f32_e32 v155, 1.0, v155
	v_add_f32_e32 v157, 1.0, v157
	v_rcp_f32_e32 v154, v154
	v_rcp_f32_e32 v156, v156
	v_rcp_f32_e32 v155, v155
	v_rcp_f32_e32 v157, v157
	v_pk_mul_f32 v[6:7], v[6:7], v[154:155]
	v_pk_mul_f32 v[8:9], v[8:9], v[156:157]
	v_pk_mul_f32 v[6:7], v[2:3], v[6:7]
	v_pk_mul_f32 v[8:9], v[4:5], v[8:9]
	v_cvt_pk_bf16_f32 v190, v6, v7
	v_cvt_pk_bf16_f32 v191, v8, v9
	global_store_dwordx4 v[236:237], v[188:191], off nt
	s_cbranch_vccz .LBB0_277
	s_and_b64 vcc, exec, s[18:19]
	s_cbranch_vccz .LBB0_278
	s_barrier
	s_branch .LBB0_278
